# filter-MLP weight staging (w1/w2 -> LDS at phase start): 16 loads per trip issued together instead of 8 load-pair/wait/write steps
# baseline (speedup 1.0000x reference)
; __device__ __forceinline__ void ph_filtergen(KP p, int l, unsigned char* sm, int wv) {
;     ...
;     for (int i = tid; i < 33 * 64; i += 512) w1s[i] = p->fw1[l * 33 * 64 + i];
;     for (int i = tid; i < 64 * 64; i += 512) w2s[i] = p->fw2[l * 4096 + i];
.LBB0_859:
	v_add_u32_e32 v8, s28, v2
	v_add_u32_e32 v10, s28, v3
	v_ashrrev_i32_e32 v9, 31, v8
	v_ashrrev_i32_e32 v11, 31, v10
	s_waitcnt lgkmcnt(0)
	v_lshl_add_u64 v[8:9], v[8:9], 2, s[14:15]
	v_lshl_add_u64 v[10:11], v[10:11], 2, s[14:15]
	global_load_dword v96, v[8:9], off
	s_nop 0
	global_load_dword v97, v[10:11], off
	v_add_u32_e32 v10, s38, v3
	v_ashrrev_i32_e32 v11, 31, v10
	v_lshl_add_u64 v[10:11], v[10:11], 2, s[14:15]
	v_add_u32_e32 v5, -8, v5
	s_add_i32 s51, s51, 16
	v_cmp_eq_u32_e32 vcc, 0, v5
	s_or_b64 s[36:37], vcc, s[36:37]
	v_add_u32_e32 v8, s31, v2
	v_ashrrev_i32_e32 v9, 31, v8
	v_lshl_add_u64 v[8:9], v[8:9], 2, s[14:15]
	global_load_dword v98, v[8:9], off
	s_nop 0
	global_load_dword v99, v[10:11], off
	v_add_u32_e32 v10, s40, v3
	v_ashrrev_i32_e32 v11, 31, v10
	v_lshl_add_u64 v[10:11], v[10:11], 2, s[14:15]
	v_add_u32_e32 v8, s39, v2
	v_ashrrev_i32_e32 v9, 31, v8
	v_lshl_add_u64 v[8:9], v[8:9], 2, s[14:15]
	global_load_dword v100, v[8:9], off
	s_nop 0
	global_load_dword v101, v[10:11], off
	v_add_u32_e32 v10, s42, v3
	v_ashrrev_i32_e32 v11, 31, v10
	v_lshl_add_u64 v[10:11], v[10:11], 2, s[14:15]
	v_add_u32_e32 v8, s41, v2
	v_ashrrev_i32_e32 v9, 31, v8
	v_lshl_add_u64 v[8:9], v[8:9], 2, s[14:15]
	global_load_dword v102, v[8:9], off
	s_nop 0
	global_load_dword v103, v[10:11], off
	v_add_u32_e32 v10, s44, v3
	v_ashrrev_i32_e32 v11, 31, v10
	v_lshl_add_u64 v[10:11], v[10:11], 2, s[14:15]
	v_add_u32_e32 v8, s43, v2
	v_ashrrev_i32_e32 v9, 31, v8
	v_lshl_add_u64 v[8:9], v[8:9], 2, s[14:15]
	global_load_dword v104, v[8:9], off
	s_nop 0
	global_load_dword v105, v[10:11], off
	v_add_u32_e32 v10, s46, v3
	v_ashrrev_i32_e32 v11, 31, v10
	v_lshl_add_u64 v[10:11], v[10:11], 2, s[14:15]
	v_add_u32_e32 v8, s45, v2
	v_ashrrev_i32_e32 v9, 31, v8
	v_lshl_add_u64 v[8:9], v[8:9], 2, s[14:15]
	global_load_dword v106, v[8:9], off
	s_nop 0
	global_load_dword v107, v[10:11], off
	v_add_u32_e32 v10, s48, v3
	v_ashrrev_i32_e32 v11, 31, v10
	v_lshl_add_u64 v[10:11], v[10:11], 2, s[14:15]
	v_add_u32_e32 v8, s47, v2
	v_ashrrev_i32_e32 v9, 31, v8
	v_lshl_add_u64 v[8:9], v[8:9], 2, s[14:15]
	global_load_dword v108, v[8:9], off
	s_nop 0
	global_load_dword v109, v[10:11], off
	v_add_u32_e32 v10, s50, v3
	v_ashrrev_i32_e32 v11, 31, v10
	v_lshl_add_u64 v[10:11], v[10:11], 2, s[14:15]
	v_add_u32_e32 v3, 0x2000, v3
	v_add_u32_e32 v8, s49, v2
	v_ashrrev_i32_e32 v9, 31, v8
	v_lshl_add_u64 v[8:9], v[8:9], 2, s[14:15]
	global_load_dword v110, v[8:9], off
	s_nop 0
	global_load_dword v111, v[10:11], off
	v_add_u32_e32 v2, 0x2000, v2
	s_waitcnt vmcnt(0)
	ds_write2st64_b32 v6, v96, v97 offset1:8
	ds_write2st64_b32 v6, v98, v99 offset0:16 offset1:24
	ds_write2st64_b32 v6, v100, v101 offset0:32 offset1:40
	ds_write2st64_b32 v6, v102, v103 offset0:48 offset1:56
	ds_write2st64_b32 v6, v104, v105 offset0:64 offset1:72
	ds_write2st64_b32 v6, v106, v107 offset0:80 offset1:88
	ds_write2st64_b32 v6, v108, v109 offset0:96 offset1:104
	ds_write2st64_b32 v6, v110, v111 offset0:112 offset1:120
	v_add_u32_e32 v6, 0x8000, v6
	v_mov_b32_e32 v7, s51
	s_andn2_b64 exec, exec, s[36:37]
	s_cbranch_execnz .LBB0_859
	s_or_b64 exec, exec, s[36:37]
